# scan state-update stage: MFMA B-operand LDS reads double-buffered (issued one MFMA ahead, lgkmcnt(2) instead of read-wait-MFMA serial chain)
# speedup vs baseline: 1.0086x; 1.0086x over previous
.LBB0_484:
	v_mov_b32_e32 v89, v106
	v_mov_b32_e32 v56, v105
	v_mov_b32_e32 v40, v104
	s_bfe_i32 s0, s42, 0x10000
	s_waitcnt lgkmcnt(0)
	s_barrier
	s_and_b32 s50, s42, 1
	s_and_b32 s49, s0, 0x17600
	s_add_i32 s42, s42, 1
	v_lshlrev_b32_e32 v41, 6, v40
	v_lshlrev_b32_e32 v40, 3, v40
	s_add_u32 s0, s43, s2
	v_and_b32_e32 v41, 0xfffffc00, v41
	v_and_b32_e32 v40, 0x78, v40
	s_addc_u32 s1, s48, s3
	v_or3_b32 v172, v41, v40, s39
	v_lshl_add_u64 v[44:45], v[172:173], 1, s[0:1]
	s_mov_b32 s0, 0x1c020000
	v_add_co_u32_e64 v40, s[0:1], s0, v44
	s_cmp_eq_u32 s50, 0
	s_nop 0
	v_addc_co_u32_e64 v41, s[0:1], 0, v45, s[0:1]
	s_mov_b32 s0, 0x1c030000
	global_load_dwordx4 v[48:51], v[40:41], off
	v_add_co_u32_e64 v40, s[0:1], s0, v44
	v_ashrrev_i32_e32 v57, 2, v56
	s_nop 0
	v_addc_co_u32_e64 v41, s[0:1], 0, v45, s[0:1]
	s_mov_b32 s0, 0x18020000
	global_load_dwordx4 v[52:55], v[40:41], off
	v_add_co_u32_e64 v40, s[0:1], s0, v44
	v_lshlrev_b32_e32 v56, 2, v56
	s_nop 0
	v_addc_co_u32_e64 v41, s[0:1], 0, v45, s[0:1]
	s_mov_b32 s0, 0x18030000
	s_nop 0
	v_add_co_u32_e64 v44, s[0:1], s0, v44
	s_cselect_b32 s50, 0x20200, s65
	s_nop 0
	v_addc_co_u32_e64 v45, s[0:1], 0, v45, s[0:1]
	v_and_b32_e32 v107, 12, v56
	s_cselect_b32 s1, 0x17600, 0
	s_cselect_b32 s0, s65, 0x20200
	s_add_i32 s50, s50, 0
	v_or_b32_e32 v56, s28, v107
	v_lshl_add_u32 v90, v89, 3, v57
	v_lshl_add_u32 v88, v56, 1, s50
	v_mad_u64_u32 v[58:59], s[50:51], v90, s61, v[88:89]
	v_lshlrev_b32_e32 v89, 2, v89
	v_sub_u32_e32 v132, v90, v89
	v_mad_u64_u32 v[88:89], s[50:51], v132, s61, v[88:89]
	global_load_dwordx4 v[40:43], v[40:41], off
	v_mov_b64_e32 v[110:111], s[46:47]
	global_load_dwordx4 v[44:47], v[44:45], off
	ds_read_b64_tr_b16 v[60:61], v58
	ds_read_b64_tr_b16 v[62:63], v58 offset:1088
	ds_read_b64_tr_b16 v[56:57], v58 offset:8704
	ds_read_b64_tr_b16 v[58:59], v58 offset:9792
	ds_read_b64_tr_b16 v[90:91], v88
	v_mov_b64_e32 v[108:109], s[44:45]
	s_waitcnt lgkmcnt(3)
	v_mfma_f32_16x16x32_bf16 v[116:119], v[4:7], v[60:63], 0
	s_add_i32 s1, s1, 0
	s_add_i32 s0, s0, 0
	s_waitcnt lgkmcnt(0)
	v_lshlrev_b32_e32 v89, 16, v90
	v_mul_f32_e32 v89, 0x3fb8aa3b, v89
	v_exp_f32_e32 v102, v89
	v_and_b32_e32 v89, 0xffff0000, v90
	v_mul_f32_e32 v89, 0x3fb8aa3b, v89
	v_exp_f32_e32 v103, v89
	v_lshlrev_b32_e32 v89, 16, v91
	v_mfma_f32_16x16x32_bf16 v[112:115], v[108:111], v[60:63], 0
	v_mul_f32_e32 v89, 0x3fb8aa3b, v89
	v_exp_f32_e32 v100, v89
	v_and_b32_e32 v89, 0xffff0000, v91
	ds_read_b64_tr_b16 v[90:91], v88 offset:4352
	v_mfma_f32_16x16x32_bf16 v[124:127], v[4:7], v[56:59], v[112:115]
	v_mul_f32_e32 v89, 0x3fb8aa3b, v89
	v_exp_f32_e32 v101, v89
	v_pk_add_f32 v[102:103], v[102:103], 1.0 op_sel_hi:[1,0] neg_lo:[1,0] neg_hi:[1,0]
	v_mfma_f32_16x16x32_bf16 v[128:131], v[0:3], v[56:59], v[112:115]
	s_waitcnt lgkmcnt(0)
	v_lshlrev_b32_e32 v89, 16, v90
	v_mul_f32_e32 v89, 0x3fb8aa3b, v89
	v_exp_f32_e32 v98, v89
	v_mfma_f32_16x16x32_bf16 v[112:115], v[108:111], v[56:59], v[112:115]
	v_and_b32_e32 v89, 0xffff0000, v90
	v_mul_f32_e32 v89, 0x3fb8aa3b, v89
	v_exp_f32_e32 v99, v89
	v_lshlrev_b32_e32 v89, 16, v91
	v_mul_f32_e32 v89, 0x3fb8aa3b, v89
	s_nop 2
	v_sub_f32_e32 v116, v112, v116
	v_sub_f32_e32 v117, v113, v117
	v_mul_f32_e32 v116, 0x3fb8aa3b, v116
	v_mul_f32_e32 v117, 0x3fb8aa3b, v117
	v_exp_f32_e32 v116, v116
	v_exp_f32_e32 v117, v117
	v_exp_f32_e32 v96, v89
	v_and_b32_e32 v89, 0xffff0000, v91
	ds_read_b64_tr_b16 v[90:91], v88 offset:8704
	v_pk_mul_f32 v[102:103], v[102:103], v[116:117]
	v_sub_f32_e32 v116, v114, v118
	v_sub_f32_e32 v117, v115, v119
	v_mul_f32_e32 v116, 0x3fb8aa3b, v116
	v_mul_f32_e32 v117, 0x3fb8aa3b, v117
	v_mfma_f32_16x16x32_bf16 v[120:123], v[0:3], v[60:63], 0
	v_exp_f32_e32 v116, v116
	v_exp_f32_e32 v117, v117
	v_mul_f32_e32 v89, 0x3fb8aa3b, v89
	v_exp_f32_e32 v97, v89
	s_waitcnt lgkmcnt(0)
	v_lshlrev_b32_e32 v89, 16, v90
	v_mul_f32_e32 v89, 0x3fb8aa3b, v89
	v_pk_add_f32 v[100:101], v[100:101], 1.0 op_sel_hi:[1,0] neg_lo:[1,0] neg_hi:[1,0]
	v_exp_f32_e32 v94, v89
	v_and_b32_e32 v89, 0xffff0000, v90
	v_pk_mul_f32 v[100:101], v[100:101], v[116:117]
	v_sub_f32_e32 v116, v112, v120
	v_sub_f32_e32 v117, v113, v121
	v_mul_f32_e32 v89, 0x3fb8aa3b, v89
	v_mul_f32_e32 v116, 0x3fb8aa3b, v116
	v_mul_f32_e32 v117, 0x3fb8aa3b, v117
	v_exp_f32_e32 v95, v89
	v_lshlrev_b32_e32 v89, 16, v91
	v_exp_f32_e32 v116, v116
	v_exp_f32_e32 v117, v117
	v_mul_f32_e32 v89, 0x3fb8aa3b, v89
	v_exp_f32_e32 v92, v89
	v_and_b32_e32 v89, 0xffff0000, v91
	v_mul_f32_e32 v89, 0x3fb8aa3b, v89
	v_pk_add_f32 v[98:99], v[98:99], 1.0 op_sel_hi:[1,0] neg_lo:[1,0] neg_hi:[1,0]
	v_exp_f32_e32 v93, v89
	ds_read_b64_tr_b16 v[88:89], v88 offset:13056
	v_pk_mul_f32 v[98:99], v[98:99], v[116:117]
	v_sub_f32_e32 v116, v114, v122
	v_sub_f32_e32 v117, v115, v123
	v_mul_f32_e32 v116, 0x3fb8aa3b, v116
	v_mul_f32_e32 v117, 0x3fb8aa3b, v117
	v_exp_f32_e32 v116, v116
	v_exp_f32_e32 v117, v117
	s_waitcnt lgkmcnt(0)
	v_lshlrev_b32_e32 v90, 16, v88
	v_and_b32_e32 v88, 0xffff0000, v88
	v_pk_add_f32 v[96:97], v[96:97], 1.0 op_sel_hi:[1,0] neg_lo:[1,0] neg_hi:[1,0]
	v_mul_f32_e32 v90, 0x3fb8aa3b, v90
	v_mul_f32_e32 v88, 0x3fb8aa3b, v88
	v_pk_mul_f32 v[96:97], v[96:97], v[116:117]
	v_sub_f32_e32 v116, v112, v124
	v_sub_f32_e32 v117, v113, v125
	v_sub_f32_e32 v112, v112, v128
	v_sub_f32_e32 v113, v113, v129
	v_exp_f32_e32 v90, v90
	v_exp_f32_e32 v91, v88
	v_mul_f32_e32 v112, 0x3fb8aa3b, v112
	v_mul_f32_e32 v113, 0x3fb8aa3b, v113
	v_exp_f32_e32 v112, v112
	v_exp_f32_e32 v113, v113
	v_mul_f32_e32 v116, 0x3fb8aa3b, v116
	v_mul_f32_e32 v117, 0x3fb8aa3b, v117
	v_mfma_f32_16x16x32_bf16 v[60:63], v[60:63], v[108:111], 0
	v_exp_f32_e32 v116, v116
	v_exp_f32_e32 v117, v117
	v_pk_add_f32 v[90:91], v[90:91], 1.0 op_sel_hi:[1,0] neg_lo:[1,0] neg_hi:[1,0]
	v_lshlrev_b32_e32 v88, 16, v89
	v_pk_mul_f32 v[112:113], v[90:91], v[112:113]
	v_sub_f32_e32 v90, v114, v130
	v_and_b32_e32 v89, 0xffff0000, v89
	v_pk_add_f32 v[94:95], v[94:95], 1.0 op_sel_hi:[1,0] neg_lo:[1,0] neg_hi:[1,0]
	v_mul_f32_e32 v90, 0x3fb8aa3b, v90
	v_mul_f32_e32 v88, 0x3fb8aa3b, v88
	v_mul_f32_e32 v89, 0x3fb8aa3b, v89
	v_pk_mul_f32 v[94:95], v[94:95], v[116:117]
	v_sub_f32_e32 v116, v114, v126
	v_sub_f32_e32 v117, v115, v127
	v_exp_f32_e32 v114, v90
	v_sub_f32_e32 v90, v115, v131
	v_mfma_f32_16x16x32_bf16 v[56:59], v[56:59], v[108:111], v[60:63]
	v_exp_f32_e32 v88, v88
	v_exp_f32_e32 v89, v89
	v_mul_f32_e32 v116, 0x3fb8aa3b, v116
	v_mul_f32_e32 v117, 0x3fb8aa3b, v117
	v_mul_f32_e32 v90, 0x3fb8aa3b, v90
	v_exp_f32_e32 v116, v116
	v_exp_f32_e32 v117, v117
	v_exp_f32_e32 v115, v90
	v_cvt_pk_bf16_f32 v90, v94, v95
	v_mul_f32_e32 v94, 0x3fb8aa3b, v58
	v_pk_add_f32 v[92:93], v[92:93], 1.0 op_sel_hi:[1,0] neg_lo:[1,0] neg_hi:[1,0]
	v_cvt_pk_bf16_f32 v60, v102, v103
	v_pk_add_f32 v[88:89], v[88:89], 1.0 op_sel_hi:[1,0] neg_lo:[1,0] neg_hi:[1,0]
	v_exp_f32_e32 v102, v94
	v_mul_f32_e32 v94, 0x3fb8aa3b, v59
	v_pk_mul_f32 v[92:93], v[92:93], v[116:117]
	v_pk_mul_f32 v[88:89], v[88:89], v[114:115]
	v_exp_f32_e32 v103, v94
	v_lshlrev_b32_e32 v94, 1, v107
	v_mul_lo_u32 v95, v132, s20
	v_cvt_pk_bf16_f32 v91, v92, v93
	v_cvt_pk_bf16_f32 v93, v88, v89
	v_mul_f32_e32 v88, 0x3fb8aa3b, v56
	v_mul_f32_e32 v89, 0x3fb8aa3b, v57
	v_add3_u32 v107, s1, v94, v95
	v_cvt_pk_bf16_f32 v61, v100, v101
	v_cvt_pk_bf16_f32 v62, v98, v99
	v_cvt_pk_bf16_f32 v63, v96, v97
	v_exp_f32_e32 v88, v88
	v_exp_f32_e32 v89, v89
	ds_read_b64_tr_b16 v[94:95], v107
	ds_read_b64_tr_b16 v[98:99], v107 offset:32
	ds_read_b64_tr_b16 v[96:97], v107 offset:4608
	v_pk_mul_f32 v[38:39], v[38:39], v[102:103]
	v_cvt_pk_bf16_f32 v92, v112, v113
	v_pk_mul_f32 v[36:37], v[36:37], v[88:89]
	v_pk_mul_f32 v[34:35], v[34:35], v[102:103]
	v_pk_mul_f32 v[32:33], v[32:33], v[88:89]
	s_waitcnt lgkmcnt(0)
	v_mfma_f32_16x16x32_bf16 v[36:39], v[60:63], v[94:97], v[36:39]
	ds_read_b64_tr_b16 v[94:95], v107 offset:9216
	ds_read_b64_tr_b16 v[96:97], v107 offset:13824
	ds_read_b64_tr_b16 v[100:101], v107 offset:4640
	v_pk_mul_f32 v[30:31], v[30:31], v[102:103]
	s_waitcnt lgkmcnt(1)
	v_mfma_f32_16x16x32_bf16 v[36:39], v[90:93], v[94:97], v[36:39]
	ds_read_b64_tr_b16 v[94:95], v107 offset:9248
	ds_read_b64_tr_b16 v[96:97], v107 offset:13856
	v_pk_mul_f32 v[28:29], v[28:29], v[88:89]
	v_pk_mul_f32 v[26:27], v[26:27], v[102:103]
	s_waitcnt lgkmcnt(2)
	v_mfma_f32_16x16x32_bf16 v[32:35], v[60:63], v[98:101], v[32:35]
	v_mul_f32_e64 v24, v24, v88
	v_mul_f32_e64 v25, v25, v89
	v_pk_mul_f32 v[22:23], v[22:23], v[102:103]
	v_pk_mul_f32 v[20:21], v[20:21], v[88:89]
	s_waitcnt lgkmcnt(0)
	v_mfma_f32_16x16x32_bf16 v[32:35], v[90:93], v[94:97], v[32:35]
	ds_read_b64_tr_b16 v[94:95], v107 offset:64
	ds_read_b64_tr_b16 v[96:97], v107 offset:4672
	ds_read_b64_tr_b16 v[228:229], v107 offset:9280
	ds_read_b64_tr_b16 v[230:231], v107 offset:13888
	v_pk_mul_f32 v[18:19], v[18:19], v[102:103]
	v_pk_mul_f32 v[16:17], v[16:17], v[88:89]
	s_waitcnt lgkmcnt(2)
	v_mfma_f32_16x16x32_bf16 v[28:31], v[60:63], v[94:97], v[28:31]
	ds_read_b64_tr_b16 v[94:95], v107 offset:96
	ds_read_b64_tr_b16 v[96:97], v107 offset:4704
	v_pk_mul_f32 v[14:15], v[14:15], v[102:103]
	v_pk_mul_f32 v[12:13], v[12:13], v[88:89]
	s_waitcnt lgkmcnt(2)
	v_mfma_f32_16x16x32_bf16 v[28:31], v[90:93], v[228:231], v[28:31]
	ds_read_b64_tr_b16 v[228:229], v107 offset:9312
	ds_read_b64_tr_b16 v[230:231], v107 offset:13920
	v_pk_mul_f32 v[10:11], v[10:11], v[102:103]
	v_pk_mul_f32 v[8:9], v[8:9], v[88:89]
	s_waitcnt lgkmcnt(2)
	v_mfma_f32_16x16x32_bf16 v[24:27], v[60:63], v[94:97], v[24:27]
	ds_read_b64_tr_b16 v[94:95], v107 offset:128
	ds_read_b64_tr_b16 v[96:97], v107 offset:4736
	v_pk_add_f32 v[84:85], v[84:85], v[56:57]
	v_mov_b32_e32 v56, v104
	s_waitcnt lgkmcnt(2)
	v_mfma_f32_16x16x32_bf16 v[24:27], v[90:93], v[228:231], v[24:27]
	ds_read_b64_tr_b16 v[228:229], v107 offset:9344
	ds_read_b64_tr_b16 v[230:231], v107 offset:13952
	v_pk_add_f32 v[86:87], v[86:87], v[58:59]
	s_add_i32 s1, s49, 0
	s_waitcnt lgkmcnt(2)
	v_mfma_f32_16x16x32_bf16 v[20:23], v[60:63], v[94:97], v[20:23]
	ds_read_b64_tr_b16 v[94:95], v107 offset:160
	ds_read_b64_tr_b16 v[96:97], v107 offset:4768
	s_add_u32 s2, s2, 0x20000
	s_addc_u32 s3, s3, 0
	s_waitcnt lgkmcnt(2)
	v_mfma_f32_16x16x32_bf16 v[20:23], v[90:93], v[228:231], v[20:23]
	ds_read_b64_tr_b16 v[228:229], v107 offset:9376
	ds_read_b64_tr_b16 v[230:231], v107 offset:13984
	s_cmp_eq_u32 s2, 0x1e0000
	s_waitcnt lgkmcnt(2)
	v_mfma_f32_16x16x32_bf16 v[16:19], v[60:63], v[94:97], v[16:19]
	ds_read_b64_tr_b16 v[94:95], v107 offset:192
	ds_read_b64_tr_b16 v[96:97], v107 offset:4800
	s_waitcnt lgkmcnt(2)
	v_mfma_f32_16x16x32_bf16 v[16:19], v[90:93], v[228:231], v[16:19]
	ds_read_b64_tr_b16 v[228:229], v107 offset:9408
	ds_read_b64_tr_b16 v[230:231], v107 offset:14016
	s_waitcnt lgkmcnt(2)
	v_mfma_f32_16x16x32_bf16 v[12:15], v[60:63], v[94:97], v[12:15]
	ds_read_b64_tr_b16 v[94:95], v107 offset:224
	ds_read_b64_tr_b16 v[96:97], v107 offset:4832
	s_waitcnt lgkmcnt(2)
	v_mfma_f32_16x16x32_bf16 v[12:15], v[90:93], v[228:231], v[12:15]
	s_waitcnt lgkmcnt(0)
	v_mfma_f32_16x16x32_bf16 v[8:11], v[60:63], v[94:97], v[8:11]
	ds_read_b64_tr_b16 v[60:61], v107 offset:9440
	ds_read_b64_tr_b16 v[62:63], v107 offset:14048
	s_nop 0
	v_ashrrev_i32_e32 v57, 4, v56
	v_lshlrev_b32_e32 v56, 4, v56
	s_waitcnt lgkmcnt(0)
	v_mfma_f32_16x16x32_bf16 v[8:11], v[90:93], v[60:63], v[8:11]
	v_mul_lo_u32 v58, v57, s20
	v_and_b32_e32 v56, 0xf0, v56
	v_add3_u32 v58, s1, v58, v56
	s_waitcnt vmcnt(3)
	ds_write_b128 v58, v[48:51]
	s_waitcnt vmcnt(2)
	ds_write_b128 v58, v[52:55] offset:9216
	v_mul_lo_u32 v48, v57, s61
	v_add3_u32 v48, s0, v48, v56
	s_waitcnt vmcnt(1)
	ds_write_b128 v48, v[40:43]
	s_waitcnt vmcnt(0)
	ds_write_b128 v48, v[44:47] offset:8704
	s_cbranch_scc0 .LBB0_484
	v_mov_b32_e32 v40, v105
	v_mov_b32_e32 v41, v106
	v_mov_b32_e32 v107, v104
	v_ashrrev_i32_e32 v42, 2, v40
	v_lshlrev_b32_e32 v40, 2, v40
	v_and_b32_e32 v116, 12, v40
	v_or_b32_e32 v40, s28, v116
	v_lshl_add_u32 v42, v41, 3, v42
	v_lshl_add_u32 v40, v40, 1, 0
	v_mad_u64_u32 v[46:47], s[0:1], v42, s61, v[40:41]
	v_lshlrev_b32_e32 v41, 2, v41
	v_sub_u32_e32 v117, v42, v41
	v_mad_u64_u32 v[48:49], s[0:1], v117, s61, v[40:41]
	s_waitcnt lgkmcnt(0)
	s_barrier
	ds_read_b64_tr_b16 v[50:51], v48 offset:18432
	ds_read_b64_tr_b16 v[40:41], v46 offset:18432
	ds_read_b64_tr_b16 v[42:43], v46 offset:19520
	ds_read_b64_tr_b16 v[44:45], v46 offset:27136
	ds_read_b64_tr_b16 v[46:47], v46 offset:28224
	ds_read_b64_tr_b16 v[52:53], v48 offset:22784
	ds_read_b64_tr_b16 v[60:61], v48 offset:27136
	ds_read_b64_tr_b16 v[96:97], v48 offset:31488
	s_waitcnt lgkmcnt(7)
	v_lshlrev_b32_e32 v48, 16, v50
	v_mul_f32_e32 v48, 0x3fb8aa3b, v48
	v_exp_f32_e32 v98, v48
	v_and_b32_e32 v48, 0xffff0000, v50
	v_mul_f32_e32 v48, 0x3fb8aa3b, v48
	v_exp_f32_e32 v99, v48
	v_lshlrev_b32_e32 v48, 16, v51
	v_mul_f32_e32 v48, 0x3fb8aa3b, v48
	v_exp_f32_e32 v100, v48
	v_and_b32_e32 v48, 0xffff0000, v51
	v_mul_f32_e32 v48, 0x3fb8aa3b, v48
	v_exp_f32_e32 v101, v48
	s_waitcnt lgkmcnt(2)
	v_lshlrev_b32_e32 v48, 16, v52
	v_mul_f32_e32 v48, 0x3fb8aa3b, v48
	v_exp_f32_e32 v102, v48
	v_and_b32_e32 v48, 0xffff0000, v52
	v_mul_f32_e32 v48, 0x3fb8aa3b, v48
	v_exp_f32_e32 v103, v48
	v_lshlrev_b32_e32 v48, 16, v53
	v_mul_f32_e32 v48, 0x3fb8aa3b, v48
	v_exp_f32_e32 v108, v48
	v_and_b32_e32 v48, 0xffff0000, v53
	v_mul_f32_e32 v48, 0x3fb8aa3b, v48
	v_exp_f32_e32 v109, v48
	s_waitcnt lgkmcnt(1)
	v_lshlrev_b32_e32 v48, 16, v60
	v_mul_f32_e32 v52, 0x3fb8aa3b, v48
	v_mov_b64_e32 v[50:51], s[46:47]
	v_mov_b64_e32 v[48:49], s[44:45]
	v_exp_f32_e32 v110, v52
	v_and_b32_e32 v52, 0xffff0000, v60
	v_mul_f32_e32 v52, 0x3fb8aa3b, v52
	v_exp_f32_e32 v111, v52
	v_mfma_f32_16x16x32_bf16 v[52:55], v[48:51], v[40:43], 0
	v_lshlrev_b32_e32 v56, 16, v61
	v_and_b32_e32 v60, 0xffff0000, v61
	s_waitcnt lgkmcnt(0)
	v_lshlrev_b32_e32 v88, 16, v96
	v_and_b32_e32 v92, 0xffff0000, v96
	v_mul_f32_e32 v56, 0x3fb8aa3b, v56
	v_mul_f32_e32 v60, 0x3fb8aa3b, v60
	v_mul_f32_e32 v88, 0x3fb8aa3b, v88
	v_mul_f32_e32 v92, 0x3fb8aa3b, v92
	v_exp_f32_e32 v112, v56
	v_mfma_f32_16x16x32_bf16 v[56:59], v[4:7], v[40:43], 0
	v_exp_f32_e32 v113, v60
	v_exp_f32_e32 v114, v88
	v_exp_f32_e32 v115, v92
	v_mfma_f32_16x16x32_bf16 v[60:63], v[0:3], v[40:43], 0
	v_lshlrev_b32_e32 v96, 16, v97
	v_and_b32_e32 v97, 0xffff0000, v97
	v_mul_f32_e32 v96, 0x3fb8aa3b, v96
	v_mfma_f32_16x16x32_bf16 v[88:91], v[4:7], v[44:47], v[52:55]
	v_mul_f32_e32 v97, 0x3fb8aa3b, v97
	v_exp_f32_e32 v96, v96
	v_exp_f32_e32 v97, v97
	v_mfma_f32_16x16x32_bf16 v[92:95], v[0:3], v[44:47], v[52:55]
	v_add_f32_e64 v100, -v100, 1.0
	v_add_f32_e64 v101, -v101, 1.0
	s_lshl_b64 s[0:1], s[30:31], 1
	s_or_b32 s0, s0, 0x1e0000
	v_mfma_f32_16x16x32_bf16 v[52:55], v[48:51], v[44:47], v[52:55]
	s_add_u32 s2, s36, s0
	s_addc_u32 s3, s37, s1
	s_add_u32 s30, s34, s0
	v_mfma_f32_16x16x32_bf16 v[40:43], v[40:43], v[48:51], 0
	s_addc_u32 s31, s35, s1
	s_nop 2
	v_sub_f32_e32 v56, v52, v56
	v_sub_f32_e32 v57, v53, v57
	v_sub_f32_e32 v58, v54, v58
	v_sub_f32_e32 v59, v55, v59
	v_sub_f32_e32 v60, v52, v60
	v_sub_f32_e32 v61, v53, v61
	v_sub_f32_e32 v88, v52, v88
	v_sub_f32_e32 v89, v53, v89
	v_sub_f32_e32 v52, v52, v92
	v_sub_f32_e32 v53, v53, v93
	v_mul_f32_e32 v58, 0x3fb8aa3b, v58
	v_mul_f32_e32 v59, 0x3fb8aa3b, v59
	v_sub_f32_e32 v62, v54, v62
	v_sub_f32_e32 v63, v55, v63
	v_sub_f32_e32 v90, v54, v90
	v_sub_f32_e32 v91, v55, v91
	v_mul_f32_e32 v52, 0x3fb8aa3b, v52
	v_mul_f32_e32 v53, 0x3fb8aa3b, v53
	v_sub_f32_e32 v54, v54, v94
	v_sub_f32_e32 v55, v55, v95
	v_exp_f32_e32 v58, v58
	v_exp_f32_e32 v59, v59
	v_mul_f32_e32 v60, 0x3fb8aa3b, v60
	v_mul_f32_e32 v61, 0x3fb8aa3b, v61
	v_exp_f32_e32 v52, v52
	v_exp_f32_e32 v53, v53
	v_mul_f32_e32 v54, 0x3fb8aa3b, v54
	v_mul_f32_e32 v55, 0x3fb8aa3b, v55
	v_mul_f32_e32 v56, 0x3fb8aa3b, v56
	v_mul_f32_e32 v57, 0x3fb8aa3b, v57
	v_exp_f32_e32 v60, v60
	v_exp_f32_e32 v61, v61
	v_mul_f32_e32 v62, 0x3fb8aa3b, v62
	v_mul_f32_e32 v63, 0x3fb8aa3b, v63
	v_exp_f32_e32 v54, v54
	v_exp_f32_e32 v55, v55
	v_exp_f32_e32 v56, v56
	v_exp_f32_e32 v57, v57
	v_exp_f32_e32 v62, v62
	v_exp_f32_e32 v63, v63
	v_mfma_f32_16x16x32_bf16 v[40:43], v[44:47], v[48:51], v[40:43]
	v_add_f32_e64 v92, -v114, 1.0
	v_add_f32_e64 v93, -v115, 1.0
	v_pk_mul_f32 v[58:59], v[100:101], v[58:59]
	v_pk_add_f32 v[100:101], v[102:103], 1.0 op_sel_hi:[1,0] neg_lo:[1,0] neg_hi:[1,0]
	v_mul_f32_e32 v88, 0x3fb8aa3b, v88
	v_mul_f32_e32 v89, 0x3fb8aa3b, v89
	v_pk_mul_f32 v[52:53], v[92:93], v[52:53]
	v_pk_add_f32 v[92:93], v[96:97], 1.0 op_sel_hi:[1,0] neg_lo:[1,0] neg_hi:[1,0]
	v_pk_mul_f32 v[60:61], v[100:101], v[60:61]
	v_pk_add_f32 v[100:101], v[108:109], 1.0 op_sel_hi:[1,0] neg_lo:[1,0] neg_hi:[1,0]
	v_exp_f32_e32 v88, v88
	v_exp_f32_e32 v89, v89
	v_mul_f32_e32 v90, 0x3fb8aa3b, v90
	v_mul_f32_e32 v91, 0x3fb8aa3b, v91
	v_pk_mul_f32 v[54:55], v[92:93], v[54:55]
	v_pk_add_f32 v[44:45], v[98:99], 1.0 op_sel_hi:[1,0] neg_lo:[1,0] neg_hi:[1,0]
	v_pk_mul_f32 v[62:63], v[100:101], v[62:63]
	v_exp_f32_e32 v90, v90
	v_exp_f32_e32 v91, v91
	v_pk_mul_f32 v[44:45], v[44:45], v[56:57]
	v_cvt_pk_bf16_f32 v46, v52, v53
	v_cvt_pk_bf16_f32 v47, v54, v55
	v_mul_f32_e32 v52, 0x3fb8aa3b, v40
	v_mul_f32_e32 v53, 0x3fb8aa3b, v41
	v_mul_f32_e32 v54, 0x3fb8aa3b, v42
	v_mul_f32_e32 v55, 0x3fb8aa3b, v43
	v_cvt_pk_bf16_f32 v48, v44, v45
	v_cvt_pk_bf16_f32 v49, v58, v59
	v_cvt_pk_bf16_f32 v50, v60, v61
	v_cvt_pk_bf16_f32 v51, v62, v63
	v_exp_f32_e32 v52, v52
	v_exp_f32_e32 v54, v54
	v_exp_f32_e32 v55, v55
	v_exp_f32_e32 v53, v53
	v_pk_add_f32 v[100:101], v[110:111], 1.0 op_sel_hi:[1,0] neg_lo:[1,0] neg_hi:[1,0]
	v_lshlrev_b32_e32 v56, 1, v116
	v_pk_mul_f32 v[88:89], v[100:101], v[88:89]
	v_pk_add_f32 v[100:101], v[112:113], 1.0 op_sel_hi:[1,0] neg_lo:[1,0] neg_hi:[1,0]
	v_mul_lo_u32 v57, v117, s20
	v_pk_mul_f32 v[90:91], v[100:101], v[90:91]
	v_cvt_pk_bf16_f32 v44, v88, v89
	v_cvt_pk_bf16_f32 v45, v90, v91
	v_pk_mul_f32 v[38:39], v[38:39], v[54:55]
	v_pk_mul_f32 v[36:37], v[36:37], v[52:53]
	v_add3_u32 v112, 0, v56, v57
	ds_read_b64_tr_b16 v[58:59], v112 offset:4608
	ds_read_b64_tr_b16 v[56:57], v112
	ds_read_b64_tr_b16 v[60:61], v112 offset:32
	ds_read_b64_tr_b16 v[88:89], v112 offset:64
	ds_read_b64_tr_b16 v[92:93], v112 offset:96
	ds_read_b64_tr_b16 v[62:63], v112 offset:4640
	ds_read_b64_tr_b16 v[90:91], v112 offset:4672
	ds_read_b64_tr_b16 v[94:95], v112 offset:4704
	s_waitcnt lgkmcnt(6)
	v_mfma_f32_16x16x32_bf16 v[36:39], v[48:51], v[56:59], v[36:39]
	ds_read_b64_tr_b16 v[58:59], v112 offset:13824
	ds_read_b64_tr_b16 v[56:57], v112 offset:9216
	ds_read_b64_tr_b16 v[96:97], v112 offset:9248
	ds_read_b64_tr_b16 v[100:101], v112 offset:9280
	ds_read_b64_tr_b16 v[108:109], v112 offset:9312
	ds_read_b64_tr_b16 v[98:99], v112 offset:13856
	ds_read_b64_tr_b16 v[102:103], v112 offset:13888
	ds_read_b64_tr_b16 v[110:111], v112 offset:13920
	v_pk_mul_f32 v[34:35], v[34:35], v[54:55]
	v_pk_mul_f32 v[32:33], v[32:33], v[52:53]
	s_waitcnt lgkmcnt(6)
	v_mfma_f32_16x16x32_bf16 v[36:39], v[44:47], v[56:59], v[36:39]
	v_lshlrev_b32_e32 v56, 6, v107
	v_pk_mul_f32 v[30:31], v[30:31], v[54:55]
	v_pk_mul_f32 v[28:29], v[28:29], v[52:53]
	v_lshlrev_b32_e32 v57, 3, v107
	v_pk_mul_f32 v[26:27], v[26:27], v[54:55]
	v_pk_mul_f32 v[24:25], v[24:25], v[52:53]
	v_mfma_f32_16x16x32_bf16 v[32:35], v[48:51], v[60:63], v[32:35]
	v_and_b32_e32 v56, 0xfffffc00, v56
	v_and_b32_e32 v57, 0x78, v57
	v_pk_mul_f32 v[22:23], v[22:23], v[54:55]
	v_mfma_f32_16x16x32_bf16 v[28:31], v[48:51], v[88:91], v[28:31]
	v_mul_f32_e64 v20, v20, v52
	v_mul_f32_e64 v21, v21, v53
	v_or3_b32 v172, v56, v57, s39
	v_pk_mul_f32 v[18:19], v[18:19], v[54:55]
	v_mfma_f32_16x16x32_bf16 v[24:27], v[48:51], v[92:95], v[24:27]
	ds_read_b64_tr_b16 v[58:59], v112 offset:4736
	ds_read_b64_tr_b16 v[56:57], v112 offset:128
	ds_read_b64_tr_b16 v[60:61], v112 offset:160
	ds_read_b64_tr_b16 v[88:89], v112 offset:192
	ds_read_b64_tr_b16 v[92:93], v112 offset:224
	ds_read_b64_tr_b16 v[62:63], v112 offset:4768
	ds_read_b64_tr_b16 v[90:91], v112 offset:4800
	ds_read_b64_tr_b16 v[94:95], v112 offset:4832
	v_pk_mul_f32 v[16:17], v[16:17], v[52:53]
	v_pk_mul_f32 v[14:15], v[14:15], v[54:55]
	s_waitcnt lgkmcnt(6)
	v_mfma_f32_16x16x32_bf16 v[20:23], v[48:51], v[56:59], v[20:23]
	v_mul_f32_e64 v12, v12, v52
	v_mul_f32_e64 v13, v13, v53
	v_pk_mul_f32 v[10:11], v[10:11], v[54:55]
	v_pk_mul_f32 v[8:9], v[8:9], v[52:53]
	v_mfma_f32_16x16x32_bf16 v[32:35], v[44:47], v[96:99], v[32:35]
	v_mfma_f32_16x16x32_bf16 v[28:31], v[44:47], v[100:103], v[28:31]
	v_mfma_f32_16x16x32_bf16 v[24:27], v[44:47], v[108:111], v[24:27]
	ds_read_b64_tr_b16 v[58:59], v112 offset:13952
	ds_read_b64_tr_b16 v[56:57], v112 offset:9344
	ds_read_b64_tr_b16 v[96:97], v112 offset:9376
	ds_read_b64_tr_b16 v[100:101], v112 offset:9408
	ds_read_b64_tr_b16 v[108:109], v112 offset:9440
	ds_read_b64_tr_b16 v[98:99], v112 offset:13984
	ds_read_b64_tr_b16 v[102:103], v112 offset:14016
	ds_read_b64_tr_b16 v[110:111], v112 offset:14048
	v_lshlrev_b64 v[112:113], 1, v[172:173]
	s_waitcnt lgkmcnt(6)
	v_mfma_f32_16x16x32_bf16 v[20:23], v[44:47], v[56:59], v[20:23]
	v_lshl_add_u64 v[56:57], s[2:3], 0, v[112:113]
	v_mfma_f32_16x16x32_bf16 v[16:19], v[48:51], v[60:63], v[16:19]
	v_add_co_u32_e64 v60, s[0:1], s21, v56
	s_nop 1
	v_addc_co_u32_e64 v61, s[0:1], 0, v57, s[0:1]
	v_mfma_f32_16x16x32_bf16 v[12:15], v[48:51], v[88:91], v[12:15]
	v_lshl_add_u64 v[88:89], s[30:31], 0, v[112:113]
	v_add_co_u32_e64 v90, s[0:1], s21, v88
	global_load_dwordx4 v[56:59], v[56:57], off
	s_nop 0
	global_load_dwordx4 v[60:63], v[60:61], off
	v_addc_co_u32_e64 v91, s[0:1], 0, v89, s[0:1]
	v_mfma_f32_16x16x32_bf16 v[8:11], v[48:51], v[92:95], v[8:11]
	global_load_dwordx4 v[48:51], v[88:89], off
	global_load_dwordx4 v[52:55], v[90:91], off
	s_lshl_b32 s0, s38, 2
	s_or_b32 s0, s0, s29
	s_waitcnt lgkmcnt(2)
	v_mfma_f32_16x16x32_bf16 v[16:19], v[44:47], v[96:99], v[16:19]
	s_ashr_i32 s1, s0, 31
	s_lshl_b64 s[2:3], s[0:1], 16
	s_add_u32 s2, s18, s2
	s_waitcnt lgkmcnt(1)
	v_mfma_f32_16x16x32_bf16 v[12:15], v[44:47], v[100:103], v[12:15]
	s_addc_u32 s3, s19, s3
	s_waitcnt lgkmcnt(0)
	v_mfma_f32_16x16x32_bf16 v[8:11], v[44:47], v[108:111], v[8:11]
	v_mov_b32_e32 v44, v104
	s_nop 0
	v_ashrrev_i32_e32 v45, 4, v44
	v_lshlrev_b32_e32 v44, 4, v44
	v_mul_lo_u32 v46, v45, s20
	v_and_b32_e32 v44, 0xf0, v44
	v_mul_lo_u32 v45, v45, s61
	v_add3_u32 v46, s60, v46, v44
	v_add3_u32 v44, s64, v45, v44
	s_waitcnt vmcnt(3)
	ds_write_b128 v46, v[56:59]
	s_waitcnt vmcnt(2)
	ds_write_b128 v46, v[60:63] offset:9216
	s_waitcnt vmcnt(1)
	ds_write_b128 v44, v[48:51]
	s_waitcnt vmcnt(0)
	ds_write_b128 v44, v[52:55] offset:8704
	v_lshl_add_u64 v[44:45], v[66:67], 2, s[2:3]
	global_store_dword v[44:45], v36, off
	v_lshl_add_u64 v[44:45], v[68:69], 2, s[2:3]
	global_store_dword v[44:45], v37, off offset:512
	global_store_dword v[44:45], v38, off offset:1024
	global_store_dword v[44:45], v39, off offset:1536
	global_store_dword v[44:45], v32, off offset:64
	v_lshl_add_u64 v[36:37], v[70:71], 2, s[2:3]
	global_store_dword v[36:37], v33, off offset:512
	global_store_dword v[36:37], v34, off offset:1024
	global_store_dword v[36:37], v35, off offset:1536
	global_store_dword v[44:45], v28, off offset:128
	v_lshl_add_u64 v[32:33], v[72:73], 2, s[2:3]
	global_store_dword v[32:33], v29, off offset:512
	global_store_dword v[32:33], v30, off offset:1024
	global_store_dword v[32:33], v31, off offset:1536
	global_store_dword v[44:45], v24, off offset:192
	v_lshl_add_u64 v[28:29], v[74:75], 2, s[2:3]
	global_store_dword v[28:29], v25, off offset:512
	global_store_dword v[28:29], v26, off offset:1024
	global_store_dword v[28:29], v27, off offset:1536
	global_store_dword v[44:45], v20, off offset:256
	v_lshl_add_u64 v[24:25], v[76:77], 2, s[2:3]
	global_store_dword v[24:25], v21, off offset:512
	global_store_dword v[24:25], v22, off offset:1024
	global_store_dword v[24:25], v23, off offset:1536
	global_store_dword v[44:45], v16, off offset:320
	v_lshl_add_u64 v[20:21], v[78:79], 2, s[2:3]
	global_store_dword v[20:21], v17, off offset:512
	global_store_dword v[20:21], v18, off offset:1024
	global_store_dword v[20:21], v19, off offset:1536
	global_store_dword v[44:45], v12, off offset:384
	v_lshl_add_u64 v[16:17], v[80:81], 2, s[2:3]
	global_store_dword v[16:17], v13, off offset:512
	global_store_dword v[16:17], v14, off offset:1024
	global_store_dword v[16:17], v15, off offset:1536
	global_store_dword v[44:45], v8, off offset:448
	v_lshl_add_u64 v[12:13], v[82:83], 2, s[2:3]
	global_store_dword v[12:13], v9, off offset:512
	global_store_dword v[12:13], v10, off offset:1024
	global_store_dword v[12:13], v11, off offset:1536
	s_and_saveexec_b64 s[2:3], vcc
	s_cbranch_execz .LBB0_482
	v_pk_add_f32 v[10:11], v[86:87], v[42:43]
	v_pk_add_f32 v[8:9], v[84:85], v[40:41]
	v_mul_f32_e32 v10, 0x3fb8aa3b, v10
	v_mul_f32_e32 v8, 0x3fb8aa3b, v8
	v_mul_f32_e32 v9, 0x3fb8aa3b, v9
	v_mul_f32_e32 v11, 0x3fb8aa3b, v11
	v_exp_f32_e32 v8, v8
	v_exp_f32_e32 v9, v9
	v_exp_f32_e32 v10, v10
	v_exp_f32_e32 v11, v11
	s_lshl_b64 s[0:1], s[0:1], 9
	v_lshl_add_u64 v[12:13], v[64:65], 0, s[0:1]
	global_store_dwordx4 v[12:13], v[8:11], off
	s_branch .LBB0_482

.LBB0_606:
	s_mov_b32 s0, s94
	s_add_i32 s94, s94, 1
	s_lshl_b32 s1, s94, 6
	s_cmp_lg_u32 s0, 15
	s_cselect_b32 s0, s1, 0x3c0
	s_add_u32 s0, s48, s0
	v_mov_b32_e32 v128, v165
	v_mov_b32_e32 v187, v166
	s_addc_u32 s1, s49, 0
	v_mov_b32_e32 v44, v164
	s_waitcnt lgkmcnt(0)
	s_barrier
	s_lshl_b64 s[0:1], s[0:1], 11
	v_lshlrev_b32_e32 v45, 6, v44
	v_lshlrev_b32_e32 v44, 3, v44
	s_add_u32 s30, s70, s0
	v_and_b32_e32 v45, 0xfffffc00, v45
	v_and_b32_e32 v44, 0x78, v44
	s_addc_u32 s31, s71, s1
	v_or3_b32 v172, v45, v44, s93
	s_add_u32 s36, s80, s0
	s_addc_u32 s37, s81, s1
	v_lshlrev_b64 v[56:57], 1, v[172:173]
	v_lshl_add_u64 v[48:49], s[30:31], 0, v[56:57]
	v_lshl_add_u64 v[58:59], s[36:37], 0, v[56:57]
	global_load_dwordx4 v[44:47], v[48:49], off
	global_load_dwordx4 v[52:55], v[58:59], off
	v_add_co_u32_e32 v48, vcc, s21, v48
	s_add_u32 s0, s72, s0
	s_nop 0
	v_addc_co_u32_e32 v49, vcc, 0, v49, vcc
	v_lshlrev_b32_e32 v68, 2, v128
	s_addc_u32 s1, s73, s1
	v_add_co_u32_e32 v58, vcc, s21, v58
	v_ashrrev_i32_e32 v188, 2, v128
	v_and_b32_e32 v189, 12, v68
	v_addc_co_u32_e32 v59, vcc, 0, v59, vcc
	v_lshl_add_u64 v[60:61], s[0:1], 0, v[56:57]
	v_lshl_add_u32 v73, v187, 3, v188
	v_or_b32_e32 v68, s42, v189
	v_lshlrev_b32_e32 v130, 2, v187
	global_load_dwordx4 v[48:51], v[48:49], off
	v_lshl_add_u32 v72, v68, 1, s64
	global_load_dwordx4 v[64:67], v[58:59], off
	v_sub_u32_e32 v190, v73, v130
	global_load_dwordx4 v[56:59], v[60:61], off
	v_add_co_u32_e32 v60, vcc, s21, v60
	v_mad_u64_u32 v[74:75], s[0:1], v73, s61, v[72:73]
	s_nop 0
	v_addc_co_u32_e32 v61, vcc, 0, v61, vcc
	v_mad_u64_u32 v[72:73], s[0:1], v190, s61, v[72:73]
	global_load_dwordx4 v[60:63], v[60:61], off
	ds_read_b64_tr_b16 v[68:69], v74
	ds_read_b64_tr_b16 v[70:71], v74 offset:1088
	ds_read_b64_tr_b16 v[76:77], v74 offset:8704
	ds_read_b64_tr_b16 v[78:79], v74 offset:9792
	ds_read_b64_tr_b16 v[74:75], v72
	v_lshlrev_b32_e32 v82, 1, v128
	v_add_u32_e32 v80, s42, v130
	v_lshlrev_b32_e32 v172, 1, v80
	v_mul_lo_u32 v185, v128, s61
	s_waitcnt lgkmcnt(0)
	v_lshlrev_b32_e32 v73, 16, v74
	v_mul_f32_e32 v73, 0x3fb8aa3b, v73
	v_exp_f32_e32 v150, v73
	v_and_b32_e32 v73, 0xffff0000, v74
	v_mul_f32_e32 v73, 0x3fb8aa3b, v73
	v_exp_f32_e32 v151, v73
	v_lshlrev_b32_e32 v73, 16, v75
	v_mul_f32_e32 v73, 0x3fb8aa3b, v73
	v_exp_f32_e32 v148, v73
	v_and_b32_e32 v73, 0xffff0000, v75
	v_mul_f32_e32 v73, 0x3fb8aa3b, v73
	v_exp_f32_e32 v149, v73
	v_and_b32_e32 v73, 0x70, v82
	v_add_lshl_u32 v73, v73, v80, 1
	v_and_b32_e32 v73, 0xf8, v73
	v_add_u32_e32 v81, s64, v172
	v_add3_u32 v73, s66, v185, v73
	ds_read_b64 v[146:147], v73
	v_add_u32_e32 v73, v81, v185
	ds_read_b64 v[140:141], v73
	ds_read_b64_tr_b16 v[74:75], v72 offset:4352
	v_add_u32_e32 v129, 0x1100, v185
	v_add_u32_e32 v186, 0x2200, v185
	v_add_u32_e32 v131, 0x3300, v185
	v_mfma_f32_16x16x32_bf16 v[192:195], v[4:7], v[68:71], 0
	s_waitcnt lgkmcnt(0)
	v_lshlrev_b32_e32 v73, 16, v74
	v_mul_f32_e32 v73, 0x3fb8aa3b, v73
	v_exp_f32_e32 v154, v73
	v_and_b32_e32 v73, 0xffff0000, v74
	v_mul_f32_e32 v73, 0x3fb8aa3b, v73
	v_exp_f32_e32 v155, v73
	v_lshlrev_b32_e32 v73, 16, v75
	v_mul_f32_e32 v73, 0x3fb8aa3b, v73
	v_exp_f32_e32 v152, v73
	v_and_b32_e32 v73, 0xffff0000, v75
	v_mul_f32_e32 v73, 0x3fb8aa3b, v73
	v_exp_f32_e32 v153, v73
	v_add_u32_e32 v73, 32, v82
	v_and_b32_e32 v73, 0x70, v73
	v_add_lshl_u32 v73, v73, v80, 1
	v_and_b32_e32 v73, 0xf8, v73
	v_add3_u32 v73, s66, v129, v73
	ds_read_b64 v[142:143], v73
	v_add_u32_e32 v73, v81, v129
	ds_read_b64 v[136:137], v73
	ds_read_b64_tr_b16 v[74:75], v72 offset:8704
	v_mfma_f32_16x16x32_bf16 v[196:199], v[0:3], v[68:71], 0
	v_add_f32_e64 v148, -v148, 1.0
	v_add_f32_e64 v149, -v149, 1.0
	s_andn2_b64 vcc, exec, s[34:35]
	s_mov_b64 s[30:31], s[18:19]
	s_waitcnt lgkmcnt(0)
	v_lshlrev_b32_e32 v73, 16, v74
	v_mul_f32_e32 v73, 0x3fb8aa3b, v73
	v_exp_f32_e32 v158, v73
	v_and_b32_e32 v73, 0xffff0000, v74
	v_mul_f32_e32 v73, 0x3fb8aa3b, v73
	v_exp_f32_e32 v159, v73
	v_lshlrev_b32_e32 v73, 16, v75
	v_mul_f32_e32 v73, 0x3fb8aa3b, v73
	v_exp_f32_e32 v156, v73
	v_and_b32_e32 v73, 0xffff0000, v75
	v_mul_f32_e32 v73, 0x3fb8aa3b, v73
	v_exp_f32_e32 v157, v73
	v_add_u32_e32 v73, 64, v82
	v_and_b32_e32 v73, 0x70, v73
	v_add_lshl_u32 v73, v73, v80, 1
	v_and_b32_e32 v73, 0xf8, v73
	v_add3_u32 v73, s66, v186, v73
	ds_read_b64 v[134:135], v73
	v_add_u32_e32 v73, v81, v186
	ds_read_b64 v[144:145], v73
	ds_read_b64_tr_b16 v[72:73], v72 offset:13056
	v_mfma_f32_16x16x32_bf16 v[96:99], v[68:71], v[4:7], 0
	s_waitcnt lgkmcnt(0)
	v_lshlrev_b32_e32 v74, 16, v72
	v_and_b32_e32 v72, 0xffff0000, v72
	v_mul_f32_e32 v72, 0x3fb8aa3b, v72
	v_exp_f32_e32 v163, v72
	v_lshlrev_b32_e32 v72, 16, v73
	v_mul_f32_e32 v72, 0x3fb8aa3b, v72
	v_exp_f32_e32 v160, v72
	v_and_b32_e32 v72, 0xffff0000, v73
	v_mul_f32_e32 v72, 0x3fb8aa3b, v72
	v_exp_f32_e32 v161, v72
	v_add_u32_e32 v72, 0x60, v82
	v_and_b32_e32 v72, 0x70, v72
	v_add_lshl_u32 v72, v72, v80, 1
	v_and_b32_e32 v72, 0xf8, v72
	v_add3_u32 v72, s66, v131, v72
	v_mul_f32_e32 v74, 0x3fb8aa3b, v74
	ds_read_b64 v[132:133], v72
	v_add_u32_e32 v72, v81, v131
	v_exp_f32_e32 v162, v74
	ds_read_b64 v[138:139], v72
	v_mov_b64_e32 v[74:75], s[46:47]
	v_mov_b64_e32 v[72:73], s[44:45]
	v_mfma_f32_16x16x32_bf16 v[88:91], v[68:71], v[0:3], 0
	s_nop 0
	v_mfma_f32_16x16x32_bf16 v[80:83], v[72:75], v[68:71], 0
	v_mfma_f32_16x16x32_bf16 v[220:223], v[72:75], v[76:79], v[80:83]
	v_mfma_f32_16x16x32_bf16 v[224:227], v[68:71], v[72:75], 0
	v_mfma_f32_16x16x32_bf16 v[92:95], v[68:71], v[8:11], 0
	s_nop 5
	v_sub_f32_e32 v68, v220, v192
	v_sub_f32_e32 v69, v221, v193
	v_mul_f32_e32 v68, 0x3fb8aa3b, v68
	v_mul_f32_e32 v69, 0x3fb8aa3b, v69
	v_exp_f32_e32 v68, v68
	v_exp_f32_e32 v69, v69
	v_pk_add_f32 v[70:71], v[150:151], 1.0 op_sel_hi:[1,0] neg_lo:[1,0] neg_hi:[1,0]
	v_pk_add_f32 v[150:151], v[154:155], 1.0 op_sel_hi:[1,0] neg_lo:[1,0] neg_hi:[1,0]
	v_mfma_f32_16x16x32_bf16 v[200:203], v[4:7], v[76:79], v[80:83]
	v_mul_f32_e64 v68, v70, v68
	v_mul_f32_e64 v69, v71, v69
	v_sub_f32_e32 v70, v222, v194
	v_sub_f32_e32 v71, v223, v195
	v_mul_f32_e32 v70, 0x3fb8aa3b, v70
	v_mul_f32_e32 v71, 0x3fb8aa3b, v71
	v_exp_f32_e32 v70, v70
	v_exp_f32_e32 v71, v71
	v_mfma_f32_16x16x32_bf16 v[204:207], v[0:3], v[76:79], v[80:83]
	v_sub_f32_e32 v96, v96, v92
	v_sub_f32_e32 v97, v97, v93
	v_pk_mul_f32 v[70:71], v[148:149], v[70:71]
	v_sub_f32_e32 v148, v220, v196
	v_sub_f32_e32 v149, v221, v197
	v_mul_f32_e32 v148, 0x3fb8aa3b, v148
	v_mul_f32_e32 v149, 0x3fb8aa3b, v149
	v_exp_f32_e32 v148, v148
	v_exp_f32_e32 v149, v149
	v_mfma_f32_16x16x32_bf16 v[84:87], v[76:79], v[4:7], v[224:227]
	v_sub_f32_e32 v98, v98, v94
	v_sub_f32_e32 v99, v99, v95
	v_pk_mul_f32 v[154:155], v[150:151], v[148:149]
	v_sub_f32_e32 v148, v222, v198
	v_sub_f32_e32 v149, v223, v199
	v_mul_f32_e32 v148, 0x3fb8aa3b, v148
	v_mul_f32_e32 v149, 0x3fb8aa3b, v149
	v_exp_f32_e32 v148, v148
	v_exp_f32_e32 v149, v149
	v_pk_add_f32 v[150:151], v[152:153], 1.0 op_sel_hi:[1,0] neg_lo:[1,0] neg_hi:[1,0]
	v_mfma_f32_16x16x32_bf16 v[80:83], v[76:79], v[0:3], v[224:227]
	v_med3_f32 v191, v96, s67, v218
	v_pk_mul_f32 v[152:153], v[150:151], v[148:149]
	v_sub_f32_e32 v148, v220, v200
	v_sub_f32_e32 v149, v221, v201
	v_mul_f32_e32 v148, 0x3fb8aa3b, v148
	v_mul_f32_e32 v149, 0x3fb8aa3b, v149
	v_exp_f32_e32 v148, v148
	v_exp_f32_e32 v149, v149
	v_pk_add_f32 v[150:151], v[158:159], 1.0 op_sel_hi:[1,0] neg_lo:[1,0] neg_hi:[1,0]
	v_med3_f32 v194, v97, s67, v218
	v_med3_f32 v195, v98, s67, v218
	v_pk_mul_f32 v[158:159], v[150:151], v[148:149]
	v_sub_f32_e32 v148, v222, v202
	v_sub_f32_e32 v149, v223, v203
	v_mul_f32_e32 v148, 0x3fb8aa3b, v148
	v_mul_f32_e32 v149, 0x3fb8aa3b, v149
	v_exp_f32_e32 v148, v148
	v_exp_f32_e32 v149, v149
	v_pk_add_f32 v[150:151], v[156:157], 1.0 op_sel_hi:[1,0] neg_lo:[1,0] neg_hi:[1,0]
	v_med3_f32 v196, v99, s67, v218
	v_mul_f32_e32 v96, 0x3fb8aa3b, v191
	v_pk_mul_f32 v[156:157], v[150:151], v[148:149]
	v_sub_f32_e32 v148, v220, v204
	v_sub_f32_e32 v149, v221, v205
	v_mul_f32_e32 v148, 0x3fb8aa3b, v148
	v_mul_f32_e32 v149, 0x3fb8aa3b, v149
	v_exp_f32_e32 v148, v148
	v_exp_f32_e32 v149, v149
	v_pk_add_f32 v[150:151], v[162:163], 1.0 op_sel_hi:[1,0] neg_lo:[1,0] neg_hi:[1,0]
	v_mul_f32_e32 v97, 0x3fb8aa3b, v194
	v_mul_f32_e32 v98, 0x3fb8aa3b, v195
	v_pk_mul_f32 v[162:163], v[150:151], v[148:149]
	v_sub_f32_e32 v148, v222, v206
	v_mul_f32_e32 v148, 0x3fb8aa3b, v148
	v_exp_f32_e32 v192, v148
	v_sub_f32_e32 v148, v223, v207
	v_mul_f32_e32 v148, 0x3fb8aa3b, v148
	v_exp_f32_e32 v193, v148
	v_mfma_f32_16x16x32_bf16 v[148:151], v[76:79], v[72:75], v[224:227]
	v_cvt_pk_bf16_f32 v75, v152, v153
	v_pk_add_f32 v[152:153], v[160:161], 1.0 op_sel_hi:[1,0] neg_lo:[1,0] neg_hi:[1,0]
	v_cvt_pk_bf16_f32 v73, v70, v71
	v_mfma_f32_16x16x32_bf16 v[76:79], v[76:79], v[8:11], v[224:227]
	v_mul_f32_e64 v152, v152, v192
	v_mul_f32_e64 v153, v153, v193
	v_cvt_pk_bf16_f32 v74, v154, v155
	v_cvt_pk_bf16_f32 v71, v152, v153
	v_mul_f32_e32 v152, 0x3fb8aa3b, v92
	v_exp_f32_e32 v160, v152
	s_nop 1
	v_mul_f32_e32 v152, 0x3fb8aa3b, v76
	v_exp_f32_e32 v154, v152
	v_sub_f32_e32 v152, v76, v92
	v_mul_f32_e32 v152, 0x3fb8aa3b, v152
	v_cvt_pk_bf16_f32 v72, v68, v69
	v_cvt_pk_bf16_f32 v69, v156, v157
	v_exp_f32_e32 v156, v152
	v_mul_f32_e32 v152, 0x3fb8aa3b, v93
	v_exp_f32_e32 v161, v152
	v_mul_f32_e32 v152, 0x3fb8aa3b, v77
	v_exp_f32_e32 v155, v152
	v_sub_f32_e32 v152, v77, v93
	v_sub_f32_e32 v153, v78, v94
	v_mul_f32_e32 v152, 0x3fb8aa3b, v152
	v_mul_f32_e32 v153, 0x3fb8aa3b, v153
	v_mul_f32_e32 v99, 0x3fb8aa3b, v196
	v_cvt_pk_bf16_f32 v68, v158, v159
	v_exp_f32_e32 v157, v152
	v_mul_f32_e32 v152, 0x3fb8aa3b, v94
	v_exp_f32_e32 v158, v153
	v_mul_f32_e32 v153, 0x3fb8aa3b, v95
	v_exp_f32_e32 v96, v96
	v_exp_f32_e32 v97, v97
	v_exp_f32_e32 v98, v98
	v_exp_f32_e32 v99, v99
	v_cvt_pk_bf16_f32 v70, v162, v163
	v_exp_f32_e32 v162, v152
	v_exp_f32_e32 v163, v153
	v_lshlrev_b32_e32 v192, 16, v146
	v_and_b32_e32 v193, 0xffff0000, v146
	v_lshlrev_b32_e32 v146, 16, v147
	v_and_b32_e32 v147, 0xffff0000, v147
	v_pk_mul_f32 v[96:97], v[96:97], v[192:193]
	v_pk_mul_f32 v[98:99], v[98:99], v[146:147]
	v_pk_mul_f32 v[192:193], v[160:161], v[96:97]
	v_pk_mul_f32 v[146:147], v[162:163], v[98:99]
	v_cvt_pk_bf16_f32 v192, v192, v193
	v_cvt_pk_bf16_f32 v193, v146, v147
	v_cvt_pk_bf16_f32 v96, v96, v97
	v_cvt_pk_bf16_f32 v97, v98, v99
	v_add3_u32 v197, v172, v185, 0
	ds_write2st64_b64 v197, v[192:193], v[96:97] offset1:34
	v_mul_f32_e32 v97, 0xbfb8aa3b, v191
	v_lshlrev_b32_e32 v96, 16, v140
	v_exp_f32_e32 v98, v97
	v_and_b32_e32 v97, 0xffff0000, v140
	v_mul_f32_e32 v96, 0x3fb8aa3b, v96
	v_mul_f32_e32 v97, 0x3fb8aa3b, v97
	v_exp_f32_e32 v96, v96
	v_exp_f32_e32 v97, v97
	v_mul_f32_e32 v99, 0xbfb8aa3b, v194
	v_exp_f32_e32 v99, v99
	v_sub_f32_e32 v159, v79, v95
	v_pk_add_f32 v[96:97], v[96:97], 1.0 op_sel_hi:[1,0] neg_lo:[1,0] neg_hi:[1,0]
	v_mul_f32_e32 v159, 0x3fb8aa3b, v159
	v_pk_mul_f32 v[96:97], v[96:97], v[98:99]
	v_lshlrev_b32_e32 v99, 16, v141
	v_mul_f32_e32 v99, 0x3fb8aa3b, v99
	v_exp_f32_e32 v140, v99
	v_mul_f32_e32 v99, 0xbfb8aa3b, v195
	v_exp_f32_e32 v146, v99
	v_and_b32_e32 v99, 0xffff0000, v141
	v_mul_f32_e32 v99, 0x3fb8aa3b, v99
	v_exp_f32_e32 v141, v99
	v_mul_f32_e32 v99, 0xbfb8aa3b, v196
	v_exp_f32_e32 v147, v99
	v_exp_f32_e32 v159, v159
	v_pk_add_f32 v[140:141], v[140:141], 1.0 op_sel_hi:[1,0] neg_lo:[1,0] neg_hi:[1,0]
	v_cvt_pk_bf16_f32 v98, v96, v97
	v_pk_mul_f32 v[140:141], v[140:141], v[146:147]
	v_pk_mul_f32 v[96:97], v[156:157], v[96:97]
	v_cvt_pk_bf16_f32 v99, v140, v141
	v_pk_mul_f32 v[140:141], v[158:159], v[140:141]
	v_cvt_pk_bf16_f32 v96, v96, v97
	v_cvt_pk_bf16_f32 v97, v140, v141
	v_sub_f32_e32 v88, v88, v92
	v_sub_f32_e32 v89, v89, v93
	v_sub_f32_e32 v90, v90, v94
	v_sub_f32_e32 v91, v91, v95
	ds_write2st64_b64 v197, v[98:99], v[96:97] offset0:68 offset1:85
	v_med3_f32 v96, v88, s67, v218
	v_med3_f32 v97, v89, s67, v218
	v_med3_f32 v98, v90, s67, v218
	v_med3_f32 v99, v91, s67, v218
	v_mul_f32_e32 v88, 0x3fb8aa3b, v96
	v_mul_f32_e32 v89, 0x3fb8aa3b, v97
	v_mul_f32_e32 v90, 0x3fb8aa3b, v98
	v_mul_f32_e32 v91, 0x3fb8aa3b, v99
	v_exp_f32_e32 v88, v88
	v_exp_f32_e32 v89, v89
	v_exp_f32_e32 v90, v90
	v_exp_f32_e32 v91, v91
	v_lshlrev_b32_e32 v92, 16, v142
	v_and_b32_e32 v93, 0xffff0000, v142
	v_lshlrev_b32_e32 v94, 16, v143
	v_and_b32_e32 v95, 0xffff0000, v143
	v_pk_mul_f32 v[88:89], v[88:89], v[92:93]
	v_pk_mul_f32 v[90:91], v[90:91], v[94:95]
	v_pk_mul_f32 v[92:93], v[160:161], v[88:89]
	v_pk_mul_f32 v[94:95], v[162:163], v[90:91]
	v_cvt_pk_bf16_f32 v92, v92, v93
	v_cvt_pk_bf16_f32 v93, v94, v95
	v_cvt_pk_bf16_f32 v88, v88, v89
	v_cvt_pk_bf16_f32 v89, v90, v91
	v_add3_u32 v140, v172, v129, 0
	ds_write2st64_b64 v140, v[92:93], v[88:89] offset1:34
	v_mul_f32_e32 v89, 0xbfb8aa3b, v96
	v_lshlrev_b32_e32 v88, 16, v136
	v_exp_f32_e32 v90, v89
	v_and_b32_e32 v89, 0xffff0000, v136
	v_mul_f32_e32 v88, 0x3fb8aa3b, v88
	v_mul_f32_e32 v89, 0x3fb8aa3b, v89
	v_exp_f32_e32 v88, v88
	v_exp_f32_e32 v89, v89
	v_mul_f32_e32 v91, 0xbfb8aa3b, v97
	v_exp_f32_e32 v91, v91
	v_sub_f32_e32 v84, v84, v76
	v_pk_add_f32 v[88:89], v[88:89], 1.0 op_sel_hi:[1,0] neg_lo:[1,0] neg_hi:[1,0]
	v_sub_f32_e32 v85, v85, v77
	v_pk_mul_f32 v[88:89], v[88:89], v[90:91]
	v_lshlrev_b32_e32 v91, 16, v137
	v_mul_f32_e32 v91, 0x3fb8aa3b, v91
	v_exp_f32_e32 v92, v91
	v_mul_f32_e32 v91, 0xbfb8aa3b, v98
	v_exp_f32_e32 v94, v91
	v_and_b32_e32 v91, 0xffff0000, v137
	v_mul_f32_e32 v91, 0x3fb8aa3b, v91
	v_exp_f32_e32 v93, v91
	v_mul_f32_e32 v91, 0xbfb8aa3b, v99
	v_exp_f32_e32 v95, v91
	v_cvt_pk_bf16_f32 v90, v88, v89
	v_pk_add_f32 v[92:93], v[92:93], 1.0 op_sel_hi:[1,0] neg_lo:[1,0] neg_hi:[1,0]
	v_pk_mul_f32 v[88:89], v[156:157], v[88:89]
	v_pk_mul_f32 v[92:93], v[92:93], v[94:95]
	v_cvt_pk_bf16_f32 v88, v88, v89
	v_cvt_pk_bf16_f32 v91, v92, v93
	v_pk_mul_f32 v[92:93], v[158:159], v[92:93]
	v_sub_f32_e32 v86, v86, v78
	v_cvt_pk_bf16_f32 v89, v92, v93
	ds_write2st64_b64 v140, v[90:91], v[88:89] offset0:68 offset1:85
	v_lshlrev_b32_e32 v88, 16, v144
	v_and_b32_e32 v89, 0xffff0000, v144
	v_mul_f32_e32 v88, 0x3fb8aa3b, v88
	v_mul_f32_e32 v89, 0x3fb8aa3b, v89
	v_med3_f32 v92, v84, s67, v218
	v_med3_f32 v93, v85, s67, v218
	v_exp_f32_e32 v88, v88
	v_exp_f32_e32 v89, v89
	v_mul_f32_e32 v84, 0x3fb8aa3b, v92
	v_mul_f32_e32 v92, 0xbfb8aa3b, v92
	v_mul_f32_e32 v85, 0x3fb8aa3b, v93
	v_mul_f32_e32 v93, 0xbfb8aa3b, v93
	v_exp_f32_e32 v92, v92
	v_exp_f32_e32 v93, v93
	v_pk_add_f32 v[88:89], v[88:89], 1.0 op_sel_hi:[1,0] neg_lo:[1,0] neg_hi:[1,0]
	v_sub_f32_e32 v87, v87, v79
	v_lshlrev_b32_e32 v90, 16, v145
	v_pk_mul_f32 v[88:89], v[88:89], v[92:93]
	v_med3_f32 v92, v86, s67, v218
	v_med3_f32 v93, v87, s67, v218
	v_and_b32_e32 v91, 0xffff0000, v145
	v_mul_f32_e32 v86, 0x3fb8aa3b, v92
	v_mul_f32_e32 v87, 0x3fb8aa3b, v93
	v_mul_f32_e32 v152, 0x3fb8aa3b, v78
	v_mul_f32_e32 v153, 0x3fb8aa3b, v79
	v_mul_f32_e32 v90, 0x3fb8aa3b, v90
	v_mul_f32_e32 v91, 0x3fb8aa3b, v91
	v_exp_f32_e32 v84, v84
	v_exp_f32_e32 v85, v85
	v_exp_f32_e32 v86, v86
	v_exp_f32_e32 v87, v87
	v_exp_f32_e32 v152, v152
	v_exp_f32_e32 v153, v153
	v_exp_f32_e32 v90, v90
	v_exp_f32_e32 v91, v91
	v_mul_f32_e32 v92, 0xbfb8aa3b, v92
	v_mul_f32_e32 v93, 0xbfb8aa3b, v93
	v_exp_f32_e32 v92, v92
	v_exp_f32_e32 v93, v93
	v_lshlrev_b32_e32 v94, 16, v134
	v_and_b32_e32 v95, 0xffff0000, v134
	v_lshlrev_b32_e32 v96, 16, v135
	v_and_b32_e32 v97, 0xffff0000, v135
	v_pk_mul_f32 v[84:85], v[84:85], v[94:95]
	v_pk_mul_f32 v[86:87], v[86:87], v[96:97]
	v_pk_mul_f32 v[94:95], v[154:155], v[84:85]
	v_pk_mul_f32 v[96:97], v[152:153], v[86:87]
	v_pk_add_f32 v[90:91], v[90:91], 1.0 op_sel_hi:[1,0] neg_lo:[1,0] neg_hi:[1,0]
	v_cvt_pk_bf16_f32 v84, v84, v85
	v_pk_mul_f32 v[90:91], v[90:91], v[92:93]
	v_cvt_pk_bf16_f32 v92, v94, v95
	v_cvt_pk_bf16_f32 v93, v96, v97
	v_cvt_pk_bf16_f32 v85, v86, v87
	v_cvt_pk_bf16_f32 v86, v88, v89
	v_add3_u32 v88, v172, v186, 0
	v_cvt_pk_bf16_f32 v87, v90, v91
	ds_write2st64_b64 v88, v[92:93], v[84:85] offset1:34
	ds_write_b64 v88, v[86:87] offset:43520
	s_waitcnt lgkmcnt(6)
	v_lshlrev_b32_e32 v84, 16, v138
	v_and_b32_e32 v85, 0xffff0000, v138
	v_sub_f32_e32 v76, v80, v76
	v_sub_f32_e32 v77, v81, v77
	v_mul_f32_e32 v84, 0x3fb8aa3b, v84
	v_mul_f32_e32 v85, 0x3fb8aa3b, v85
	v_med3_f32 v80, v76, s67, v218
	v_med3_f32 v81, v77, s67, v218
	v_sub_f32_e32 v78, v82, v78
	v_sub_f32_e32 v79, v83, v79
	v_exp_f32_e32 v84, v84
	v_exp_f32_e32 v85, v85
	v_mul_f32_e32 v76, 0x3fb8aa3b, v80
	v_mul_f32_e32 v80, 0xbfb8aa3b, v80
	v_mul_f32_e32 v77, 0x3fb8aa3b, v81
	v_mul_f32_e32 v81, 0xbfb8aa3b, v81
	v_med3_f32 v82, v78, s67, v218
	v_med3_f32 v83, v79, s67, v218
	v_lshlrev_b32_e32 v86, 16, v139
	v_and_b32_e32 v87, 0xffff0000, v139
	v_exp_f32_e32 v80, v80
	v_exp_f32_e32 v81, v81
	v_mul_f32_e32 v78, 0x3fb8aa3b, v82
	v_mul_f32_e32 v79, 0x3fb8aa3b, v83
	v_mul_f32_e32 v86, 0x3fb8aa3b, v86
	v_mul_f32_e32 v87, 0x3fb8aa3b, v87
	v_exp_f32_e32 v76, v76
	v_exp_f32_e32 v77, v77
	v_exp_f32_e32 v78, v78
	v_exp_f32_e32 v79, v79
	v_exp_f32_e32 v86, v86
	v_exp_f32_e32 v87, v87
	v_mul_f32_e32 v82, 0xbfb8aa3b, v82
	v_mul_f32_e32 v83, 0xbfb8aa3b, v83
	v_pk_add_f32 v[84:85], v[84:85], 1.0 op_sel_hi:[1,0] neg_lo:[1,0] neg_hi:[1,0]
	v_exp_f32_e32 v82, v82
	v_exp_f32_e32 v83, v83
	v_lshlrev_b32_e32 v88, 16, v132
	v_and_b32_e32 v89, 0xffff0000, v132
	v_pk_mul_f32 v[80:81], v[84:85], v[80:81]
	v_lshlrev_b32_e32 v84, 16, v133
	v_and_b32_e32 v85, 0xffff0000, v133
	v_pk_mul_f32 v[76:77], v[76:77], v[88:89]
	v_pk_mul_f32 v[78:79], v[78:79], v[84:85]
	v_pk_mul_f32 v[88:89], v[154:155], v[76:77]
	v_pk_mul_f32 v[84:85], v[152:153], v[78:79]
	v_pk_add_f32 v[86:87], v[86:87], 1.0 op_sel_hi:[1,0] neg_lo:[1,0] neg_hi:[1,0]
	v_cvt_pk_bf16_f32 v76, v76, v77
	v_pk_mul_f32 v[82:83], v[86:87], v[82:83]
	v_cvt_pk_bf16_f32 v86, v88, v89
	v_cvt_pk_bf16_f32 v87, v84, v85
	v_cvt_pk_bf16_f32 v77, v78, v79
	v_cvt_pk_bf16_f32 v78, v80, v81
	v_add3_u32 v80, v172, v131, 0
	v_cvt_pk_bf16_f32 v79, v82, v83
	ds_write2st64_b64 v80, v[86:87], v[76:77] offset1:34
	ds_write_b64 v80, v[78:79] offset:43520
	v_lshlrev_b32_e32 v92, 1, v189
	v_mul_lo_u32 v76, v190, s20
	v_mul_f32_e32 v148, 0x3fb8aa3b, v148
	v_mul_f32_e32 v149, 0x3fb8aa3b, v149
	v_mul_f32_e32 v150, 0x3fb8aa3b, v150
	v_mul_f32_e32 v151, 0x3fb8aa3b, v151
	s_waitcnt lgkmcnt(0)
	s_barrier
	v_add3_u32 v84, s60, v92, v76
	v_exp_f32_e32 v148, v148
	v_exp_f32_e32 v149, v149
	v_exp_f32_e32 v150, v150
	v_exp_f32_e32 v151, v151
	ds_read_b64_tr_b16 v[76:77], v84
	ds_read_b64_tr_b16 v[80:81], v84 offset:32
	ds_read_b64_tr_b16 v[78:79], v84 offset:4608
	v_pk_mul_f32 v[12:13], v[12:13], v[148:149]
	v_pk_mul_f32 v[16:17], v[16:17], v[148:149]
	v_pk_mul_f32 v[14:15], v[14:15], v[150:151]
	v_pk_mul_f32 v[18:19], v[18:19], v[150:151]
	v_pk_mul_f32 v[26:27], v[26:27], v[150:151]
	s_waitcnt lgkmcnt(0)
	v_mfma_f32_16x16x32_bf16 v[12:15], v[72:75], v[76:79], v[12:15]
	ds_read_b64_tr_b16 v[76:77], v84 offset:9216
	ds_read_b64_tr_b16 v[78:79], v84 offset:13824
	ds_read_b64_tr_b16 v[82:83], v84 offset:4640
	v_pk_mul_f32 v[24:25], v[24:25], v[148:149]
	s_waitcnt lgkmcnt(1)
	v_mfma_f32_16x16x32_bf16 v[12:15], v[68:71], v[76:79], v[12:15]
	ds_read_b64_tr_b16 v[76:77], v84 offset:9248
	ds_read_b64_tr_b16 v[78:79], v84 offset:13856
	v_pk_mul_f32 v[34:35], v[34:35], v[150:151]
	v_pk_mul_f32 v[32:33], v[32:33], v[148:149]
	s_waitcnt lgkmcnt(2)
	v_mfma_f32_16x16x32_bf16 v[16:19], v[72:75], v[80:83], v[16:19]
	v_mul_f32_e64 v22, v22, v150
	v_mul_f32_e64 v23, v23, v151
	v_pk_mul_f32 v[20:21], v[20:21], v[148:149]
	v_pk_mul_f32 v[30:31], v[30:31], v[150:151]
	s_waitcnt lgkmcnt(0)
	v_mfma_f32_16x16x32_bf16 v[16:19], v[68:71], v[76:79], v[16:19]
	ds_read_b64_tr_b16 v[76:77], v84 offset:64
	ds_read_b64_tr_b16 v[78:79], v84 offset:4672
	ds_read_b64_tr_b16 v[228:229], v84 offset:9280
	ds_read_b64_tr_b16 v[230:231], v84 offset:13888
	v_pk_mul_f32 v[28:29], v[28:29], v[148:149]
	v_pk_mul_f32 v[38:39], v[38:39], v[150:151]
	s_waitcnt lgkmcnt(2)
	v_mfma_f32_16x16x32_bf16 v[24:27], v[72:75], v[76:79], v[24:27]
	ds_read_b64_tr_b16 v[76:77], v84 offset:96
	ds_read_b64_tr_b16 v[78:79], v84 offset:4704
	v_pk_mul_f32 v[36:37], v[36:37], v[148:149]
	v_pk_mul_f32 v[42:43], v[42:43], v[150:151]
	s_waitcnt lgkmcnt(2)
	v_mfma_f32_16x16x32_bf16 v[24:27], v[68:71], v[228:231], v[24:27]
	ds_read_b64_tr_b16 v[228:229], v84 offset:9312
	ds_read_b64_tr_b16 v[230:231], v84 offset:13920
	v_pk_mul_f32 v[40:41], v[40:41], v[148:149]
	v_lshlrev_b32_e32 v95, 4, v187
	s_waitcnt lgkmcnt(2)
	v_mfma_f32_16x16x32_bf16 v[32:35], v[72:75], v[76:79], v[32:35]
	ds_read_b64_tr_b16 v[76:77], v84 offset:128
	ds_read_b64_tr_b16 v[78:79], v84 offset:4736
	v_add_u32_e32 v89, s84, v95
	v_add_u32_e32 v90, v89, v185
	s_waitcnt lgkmcnt(2)
	v_mfma_f32_16x16x32_bf16 v[32:35], v[68:71], v[228:231], v[32:35]
	ds_read_b64_tr_b16 v[228:229], v84 offset:9344
	ds_read_b64_tr_b16 v[230:231], v84 offset:13952
	s_waitcnt lgkmcnt(2)
	v_mfma_f32_16x16x32_bf16 v[20:23], v[72:75], v[76:79], v[20:23]
	ds_read_b64_tr_b16 v[76:77], v84 offset:160
	ds_read_b64_tr_b16 v[78:79], v84 offset:4768
	s_waitcnt lgkmcnt(2)
	v_mfma_f32_16x16x32_bf16 v[20:23], v[68:71], v[228:231], v[20:23]
	ds_read_b64_tr_b16 v[228:229], v84 offset:9376
	ds_read_b64_tr_b16 v[230:231], v84 offset:13984
	s_waitcnt lgkmcnt(2)
	v_mfma_f32_16x16x32_bf16 v[28:31], v[72:75], v[76:79], v[28:31]
	ds_read_b64_tr_b16 v[76:77], v84 offset:192
	ds_read_b64_tr_b16 v[78:79], v84 offset:4800
	s_waitcnt lgkmcnt(2)
	v_mfma_f32_16x16x32_bf16 v[28:31], v[68:71], v[228:231], v[28:31]
	ds_read_b64_tr_b16 v[228:229], v84 offset:9408
	ds_read_b64_tr_b16 v[230:231], v84 offset:14016
	s_waitcnt lgkmcnt(2)
	v_mfma_f32_16x16x32_bf16 v[36:39], v[72:75], v[76:79], v[36:39]
	ds_read_b64_tr_b16 v[76:77], v84 offset:224
	ds_read_b64_tr_b16 v[78:79], v84 offset:4832
	s_waitcnt lgkmcnt(2)
	v_mfma_f32_16x16x32_bf16 v[36:39], v[68:71], v[228:231], v[36:39]
	s_waitcnt lgkmcnt(0)
	v_mfma_f32_16x16x32_bf16 v[40:43], v[72:75], v[76:79], v[40:43]
	ds_read_b64_tr_b16 v[72:73], v84 offset:9440
	ds_read_b64_tr_b16 v[74:75], v84 offset:14048
	s_waitcnt lgkmcnt(0)
	v_mfma_f32_16x16x32_bf16 v[40:43], v[68:71], v[72:75], v[40:43]
	v_add_u32_e32 v68, s85, v128
	v_mul_lo_u32 v68, v68, s61
	v_add_u32_e32 v68, 0, v68
	v_add_u32_e32 v88, v68, v95
	ds_read_b128 v[80:83], v88 offset:17408
	ds_read_b128 v[84:87], v88 offset:17472
	ds_read_b128 v[96:99], v88 offset:17536
	ds_read_b128 v[132:135], v88 offset:17600
	ds_read_b128 v[68:71], v90
	ds_read_b128 v[72:75], v90 offset:64
	ds_read_b128 v[76:79], v90 offset:128
	ds_read_b128 v[136:139], v90 offset:192
	s_waitcnt lgkmcnt(3)
	v_mfma_f32_16x16x32_bf16 v[68:71], v[68:71], v[80:83], 0
	v_add_u32_e32 v90, v89, v129
	s_waitcnt lgkmcnt(2)
	v_mfma_f32_16x16x32_bf16 v[68:71], v[72:75], v[84:87], v[68:71]
	s_waitcnt lgkmcnt(1)
	v_mfma_f32_16x16x32_bf16 v[68:71], v[76:79], v[96:99], v[68:71]
	s_waitcnt lgkmcnt(0)
	v_mfma_f32_16x16x32_bf16 v[68:71], v[136:139], v[132:135], v[68:71]
	ds_read_b128 v[72:75], v90
	ds_read_b128 v[76:79], v90 offset:64
	ds_read_b128 v[136:139], v90 offset:128
	ds_read_b128 v[140:143], v90 offset:192
	v_add_u32_e32 v90, v89, v186
	v_add_u32_e32 v89, v89, v131
	s_waitcnt lgkmcnt(3)
	v_mfma_f32_16x16x32_bf16 v[72:75], v[72:75], v[80:83], 0
	s_waitcnt lgkmcnt(2)
	v_mfma_f32_16x16x32_bf16 v[72:75], v[76:79], v[84:87], v[72:75]
	s_waitcnt lgkmcnt(1)
	v_mfma_f32_16x16x32_bf16 v[72:75], v[136:139], v[96:99], v[72:75]
	s_waitcnt lgkmcnt(0)
	v_mfma_f32_16x16x32_bf16 v[72:75], v[140:143], v[132:135], v[72:75]
	ds_read_b128 v[76:79], v90
	ds_read_b128 v[136:139], v90 offset:64
	ds_read_b128 v[140:143], v90 offset:128
	ds_read_b128 v[144:147], v90 offset:192
	s_waitcnt lgkmcnt(3)
	v_mfma_f32_16x16x32_bf16 v[76:79], v[76:79], v[80:83], 0
	s_waitcnt lgkmcnt(2)
	v_mfma_f32_16x16x32_bf16 v[76:79], v[136:139], v[84:87], v[76:79]
	s_waitcnt lgkmcnt(1)
	v_mfma_f32_16x16x32_bf16 v[76:79], v[140:143], v[96:99], v[76:79]
	s_waitcnt lgkmcnt(0)
	v_mfma_f32_16x16x32_bf16 v[76:79], v[144:147], v[132:135], v[76:79]
	ds_read_b128 v[136:139], v89
	ds_read_b128 v[140:143], v89 offset:64
	ds_read_b128 v[144:147], v89 offset:128
	ds_read_b128 v[148:151], v89 offset:192
	s_waitcnt lgkmcnt(3)
	v_mfma_f32_16x16x32_bf16 v[80:83], v[136:139], v[80:83], 0
	s_waitcnt lgkmcnt(2)
	v_mfma_f32_16x16x32_bf16 v[80:83], v[140:143], v[84:87], v[80:83]
	v_cndmask_b32_e64 v84, 0, 1, s[34:35]
	v_or_b32_e32 v85, 2, v130
	v_cmp_ne_u32_e64 s[0:1], 1, v84
	s_waitcnt lgkmcnt(1)
	v_mfma_f32_16x16x32_bf16 v[80:83], v[144:147], v[96:99], v[80:83]
	v_cmp_le_i32_e64 s[36:37], v85, v128
	s_waitcnt lgkmcnt(0)
	v_mfma_f32_16x16x32_bf16 v[80:83], v[148:151], v[132:135], v[80:83]
	s_cbranch_vccnz .LBB0_608
	s_and_b64 s[30:31], s[38:39], s[36:37]
	s_andn2_b64 s[36:37], s[18:19], exec
	s_and_b64 s[30:31], s[30:31], exec
	s_or_b64 s[30:31], s[36:37], s[30:31]
